# attention main loops (10 QK^T blocks): K-fragment LDS reads software-pipelined through a 6-deep rolling window of dead registers with counted lgkmcnt waits instead of read/drain/MFMA 16 times
# speedup vs baseline: 1.0073x; 1.0043x over previous
.LBB0_1482:
	v_cndmask_b32_e64 v1, 0, 1, s[30:31]
	v_cmp_ne_u32_e64 s[4:5], 1, v1
	s_andn2_b64 vcc, exec, s[30:31]
	s_cbranch_vccnz .LBB0_1484
	ds_read_b128 v[100:103], v224
	ds_read_b128 v[104:107], v224 offset:32
	ds_read_b128 v[108:111], v224 offset:64
	s_waitcnt vmcnt(1)
	ds_read_b128 v[112:115], v224 offset:96
	ds_read_b128 v[84:87], v224 offset:128
	ds_read_b128 v[88:91], v224 offset:160
	ds_read_b128 v[92:95], v224 offset:192
	ds_read_b128 v[96:99], v224 offset:224
	ds_read_b128 v[2:5], v226 offset:49152
	ds_read_b128 v[6:9], v226 offset:57344
	ds_read_b128 v[10:13], v227 offset:49152
	ds_read_b128 v[80:83], v227 offset:57344
	ds_read_b128 v[116:119], v228 offset:49152
	ds_read_b128 v[120:123], v228 offset:57344
	s_waitcnt lgkmcnt(5)
	v_mfma_f32_32x32x16_bf16 v[100:115], v[2:5], v[172:175], v[100:115]
	ds_read_b128 v[2:5], v229 offset:49152
	s_waitcnt lgkmcnt(5)
	v_mfma_f32_32x32x16_bf16 v[84:99], v[6:9], v[172:175], v[84:99]
	ds_read_b128 v[6:9], v229 offset:57344
	s_waitcnt lgkmcnt(5)
	v_mfma_f32_32x32x16_bf16 v[100:115], v[10:13], v[168:171], v[100:115]
	ds_read_b128 v[10:13], v226 offset:49280
	s_waitcnt lgkmcnt(5)
	v_mfma_f32_32x32x16_bf16 v[84:99], v[80:83], v[168:171], v[84:99]
	ds_read_b128 v[80:83], v226 offset:57472
	s_waitcnt lgkmcnt(5)
	v_mfma_f32_32x32x16_bf16 v[100:115], v[116:119], v[164:167], v[100:115]
	ds_read_b128 v[116:119], v227 offset:49280
	s_waitcnt lgkmcnt(5)
	v_mfma_f32_32x32x16_bf16 v[84:99], v[120:123], v[164:167], v[84:99]
	ds_read_b128 v[120:123], v227 offset:57472
	s_waitcnt lgkmcnt(5)
	v_mfma_f32_32x32x16_bf16 v[100:115], v[2:5], v[160:163], v[100:115]
	ds_read_b128 v[2:5], v228 offset:49280
	s_waitcnt lgkmcnt(5)
	v_mfma_f32_32x32x16_bf16 v[84:99], v[6:9], v[160:163], v[84:99]
	ds_read_b128 v[6:9], v228 offset:57472
	s_waitcnt lgkmcnt(5)
	v_mfma_f32_32x32x16_bf16 v[100:115], v[10:13], v[156:159], v[100:115]
	ds_read_b128 v[10:13], v229 offset:49280
	s_waitcnt lgkmcnt(5)
	v_mfma_f32_32x32x16_bf16 v[84:99], v[80:83], v[156:159], v[84:99]
	ds_read_b128 v[80:83], v229 offset:57472
	s_waitcnt lgkmcnt(5)
	v_mfma_f32_32x32x16_bf16 v[100:115], v[116:119], v[152:155], v[100:115]
	s_waitcnt lgkmcnt(4)
	v_mfma_f32_32x32x16_bf16 v[84:99], v[120:123], v[152:155], v[84:99]
	s_waitcnt lgkmcnt(3)
	v_mfma_f32_32x32x16_bf16 v[100:115], v[2:5], v[148:151], v[100:115]
	s_waitcnt lgkmcnt(2)
	v_mfma_f32_32x32x16_bf16 v[84:99], v[6:9], v[148:151], v[84:99]
	s_waitcnt lgkmcnt(1)
	v_mfma_f32_32x32x16_bf16 v[100:115], v[10:13], v[144:147], v[100:115]
	s_waitcnt lgkmcnt(0)
	v_mfma_f32_32x32x16_bf16 v[84:99], v[80:83], v[144:147], v[84:99]
	s_branch .LBB0_1485

.LBB0_1493:
	v_cndmask_b32_e64 v234, v1, v192, s[6:7]
	v_mul_f32_e32 v192, 0xbe0293ee, v234
	v_fmamk_f32 v1, v100, 0x3e0293ee, v192
	v_fmamk_f32 v2, v101, 0x3e0293ee, v192
	v_fmamk_f32 v3, v102, 0x3e0293ee, v192
	v_fmamk_f32 v4, v103, 0x3e0293ee, v192
	v_fmamk_f32 v5, v104, 0x3e0293ee, v192
	v_fmamk_f32 v6, v105, 0x3e0293ee, v192
	v_fmamk_f32 v7, v106, 0x3e0293ee, v192
	v_fmamk_f32 v8, v107, 0x3e0293ee, v192
	v_fmamk_f32 v9, v108, 0x3e0293ee, v192
	v_fmamk_f32 v10, v109, 0x3e0293ee, v192
	v_fmamk_f32 v11, v110, 0x3e0293ee, v192
	v_fmamk_f32 v12, v111, 0x3e0293ee, v192
	v_fmamk_f32 v13, v112, 0x3e0293ee, v192
	v_fmamk_f32 v14, v113, 0x3e0293ee, v192
	v_fmamk_f32 v15, v114, 0x3e0293ee, v192
	v_fmamk_f32 v112, v115, 0x3e0293ee, v192
	v_fmamk_f32 v100, v84, 0x3e0293ee, v192
	v_fmamk_f32 v101, v85, 0x3e0293ee, v192
	v_fmamk_f32 v102, v86, 0x3e0293ee, v192
	v_fmamk_f32 v103, v87, 0x3e0293ee, v192
	v_fmamk_f32 v104, v88, 0x3e0293ee, v192
	v_fmamk_f32 v105, v89, 0x3e0293ee, v192
	v_fmamk_f32 v106, v90, 0x3e0293ee, v192
	v_fmamk_f32 v107, v91, 0x3e0293ee, v192
	v_fmamk_f32 v108, v92, 0x3e0293ee, v192
	v_fmamk_f32 v109, v93, 0x3e0293ee, v192
	v_fmamk_f32 v110, v94, 0x3e0293ee, v192
	v_fmamk_f32 v111, v95, 0x3e0293ee, v192
	v_exp_f32_e32 v80, v1
	v_exp_f32_e32 v81, v2
	v_exp_f32_e32 v82, v3
	v_exp_f32_e32 v83, v4
	v_exp_f32_e32 v84, v5
	v_exp_f32_e32 v85, v6
	v_exp_f32_e32 v86, v7
	v_exp_f32_e32 v87, v8
	v_exp_f32_e32 v88, v9
	v_exp_f32_e32 v89, v10
	v_exp_f32_e32 v90, v11
	v_exp_f32_e32 v91, v12
	v_exp_f32_e32 v92, v13
	v_exp_f32_e32 v93, v14
	v_exp_f32_e32 v94, v15
	v_exp_f32_e32 v95, v112
	v_fmamk_f32 v193, v96, 0x3e0293ee, v192
	v_fmamk_f32 v194, v97, 0x3e0293ee, v192
	v_fmamk_f32 v195, v98, 0x3e0293ee, v192
	v_fmac_f32_e32 v192, 0x3e0293ee, v99
	s_waitcnt lgkmcnt(0)
	s_barrier
	s_and_b64 vcc, exec, s[4:5]
	s_cbranch_vccnz .LBB0_1495
	ds_read_b128 v[128:131], v224 offset:256
	ds_read_b128 v[132:135], v224 offset:288
	ds_read_b128 v[136:139], v224 offset:320
	ds_read_b128 v[140:143], v224 offset:352
	ds_read_b128 v[112:115], v224 offset:384
	ds_read_b128 v[116:119], v224 offset:416
	ds_read_b128 v[120:123], v224 offset:448
	ds_read_b128 v[124:127], v224 offset:480
	ds_read_b128 v[2:5], v226 offset:32768
	ds_read_b128 v[6:9], v226 offset:40960
	ds_read_b128 v[10:13], v227 offset:32768
	ds_read_b128 v[96:99], v227 offset:40960
	ds_read_b128 v[236:239], v228 offset:32768
	ds_read_b128 v[240:243], v228 offset:40960
	s_waitcnt lgkmcnt(5)
	v_mfma_f32_32x32x16_bf16 v[128:143], v[2:5], v[172:175], v[128:143]
	ds_read_b128 v[2:5], v229 offset:32768
	s_waitcnt lgkmcnt(5)
	v_mfma_f32_32x32x16_bf16 v[112:127], v[6:9], v[172:175], v[112:127]
	ds_read_b128 v[6:9], v229 offset:40960
	s_waitcnt lgkmcnt(5)
	v_mfma_f32_32x32x16_bf16 v[128:143], v[10:13], v[168:171], v[128:143]
	ds_read_b128 v[10:13], v226 offset:32896
	s_waitcnt lgkmcnt(5)
	v_mfma_f32_32x32x16_bf16 v[112:127], v[96:99], v[168:171], v[112:127]
	ds_read_b128 v[96:99], v226 offset:41088
	s_waitcnt lgkmcnt(5)
	v_mfma_f32_32x32x16_bf16 v[128:143], v[236:239], v[164:167], v[128:143]
	ds_read_b128 v[236:239], v227 offset:32896
	s_waitcnt lgkmcnt(5)
	v_mfma_f32_32x32x16_bf16 v[112:127], v[240:243], v[164:167], v[112:127]
	ds_read_b128 v[240:243], v227 offset:41088
	s_waitcnt lgkmcnt(5)
	v_mfma_f32_32x32x16_bf16 v[128:143], v[2:5], v[160:163], v[128:143]
	ds_read_b128 v[2:5], v228 offset:32896
	s_waitcnt lgkmcnt(5)
	v_mfma_f32_32x32x16_bf16 v[112:127], v[6:9], v[160:163], v[112:127]
	ds_read_b128 v[6:9], v228 offset:41088
	s_waitcnt lgkmcnt(5)
	v_mfma_f32_32x32x16_bf16 v[128:143], v[10:13], v[156:159], v[128:143]
	ds_read_b128 v[10:13], v229 offset:32896
	s_waitcnt lgkmcnt(5)
	v_mfma_f32_32x32x16_bf16 v[112:127], v[96:99], v[156:159], v[112:127]
	ds_read_b128 v[96:99], v229 offset:41088
	s_waitcnt lgkmcnt(5)
	v_mfma_f32_32x32x16_bf16 v[128:143], v[236:239], v[152:155], v[128:143]
	s_waitcnt lgkmcnt(4)
	v_mfma_f32_32x32x16_bf16 v[112:127], v[240:243], v[152:155], v[112:127]
	s_waitcnt lgkmcnt(3)
	v_mfma_f32_32x32x16_bf16 v[128:143], v[2:5], v[148:151], v[128:143]
	s_waitcnt lgkmcnt(2)
	v_mfma_f32_32x32x16_bf16 v[112:127], v[6:9], v[148:151], v[112:127]
	s_waitcnt lgkmcnt(1)
	v_mfma_f32_32x32x16_bf16 v[128:143], v[10:13], v[144:147], v[128:143]
	s_waitcnt lgkmcnt(0)
	v_mfma_f32_32x32x16_bf16 v[112:127], v[96:99], v[144:147], v[112:127]
	s_branch .LBB0_1496

.LBB0_2854:
	v_cndmask_b32_e64 v1, 0, 1, s[20:21]
	v_cmp_ne_u32_e64 s[38:39], 1, v1
	s_andn2_b64 vcc, exec, s[20:21]
	s_cbranch_vccnz .LBB0_2856
	ds_read_b128 v[100:103], v224
	ds_read_b128 v[104:107], v224 offset:32
	ds_read_b128 v[108:111], v224 offset:64
	s_waitcnt vmcnt(3)
	ds_read_b128 v[112:115], v224 offset:96
	ds_read_b128 v[84:87], v224 offset:128
	ds_read_b128 v[88:91], v224 offset:160
	ds_read_b128 v[92:95], v224 offset:192
	ds_read_b128 v[96:99], v224 offset:224
	ds_read_b128 v[2:5], v226 offset:49152
	ds_read_b128 v[6:9], v226 offset:57344
	ds_read_b128 v[10:13], v227 offset:49152
	ds_read_b128 v[80:83], v227 offset:57344
	ds_read_b128 v[116:119], v228 offset:49152
	ds_read_b128 v[120:123], v228 offset:57344
	s_waitcnt lgkmcnt(5)
	v_mfma_f32_32x32x16_bf16 v[100:115], v[2:5], v[172:175], v[100:115]
	ds_read_b128 v[2:5], v229 offset:49152
	s_waitcnt lgkmcnt(5)
	v_mfma_f32_32x32x16_bf16 v[84:99], v[6:9], v[172:175], v[84:99]
	ds_read_b128 v[6:9], v229 offset:57344
	s_waitcnt lgkmcnt(5)
	v_mfma_f32_32x32x16_bf16 v[100:115], v[10:13], v[168:171], v[100:115]
	ds_read_b128 v[10:13], v226 offset:49280
	s_waitcnt lgkmcnt(5)
	v_mfma_f32_32x32x16_bf16 v[84:99], v[80:83], v[168:171], v[84:99]
	ds_read_b128 v[80:83], v226 offset:57472
	s_waitcnt lgkmcnt(5)
	v_mfma_f32_32x32x16_bf16 v[100:115], v[116:119], v[164:167], v[100:115]
	ds_read_b128 v[116:119], v227 offset:49280
	s_waitcnt lgkmcnt(5)
	v_mfma_f32_32x32x16_bf16 v[84:99], v[120:123], v[164:167], v[84:99]
	ds_read_b128 v[120:123], v227 offset:57472
	s_waitcnt lgkmcnt(5)
	v_mfma_f32_32x32x16_bf16 v[100:115], v[2:5], v[160:163], v[100:115]
	ds_read_b128 v[2:5], v228 offset:49280
	s_waitcnt lgkmcnt(5)
	v_mfma_f32_32x32x16_bf16 v[84:99], v[6:9], v[160:163], v[84:99]
	ds_read_b128 v[6:9], v228 offset:57472
	s_waitcnt lgkmcnt(5)
	v_mfma_f32_32x32x16_bf16 v[100:115], v[10:13], v[156:159], v[100:115]
	ds_read_b128 v[10:13], v229 offset:49280
	s_waitcnt lgkmcnt(5)
	v_mfma_f32_32x32x16_bf16 v[84:99], v[80:83], v[156:159], v[84:99]
	ds_read_b128 v[80:83], v229 offset:57472
	s_waitcnt vmcnt(2) lgkmcnt(5)
	v_mfma_f32_32x32x16_bf16 v[100:115], v[116:119], v[152:155], v[100:115]
	s_waitcnt lgkmcnt(4)
	v_mfma_f32_32x32x16_bf16 v[84:99], v[120:123], v[152:155], v[84:99]
	s_waitcnt vmcnt(1) lgkmcnt(3)
	v_mfma_f32_32x32x16_bf16 v[100:115], v[2:5], v[148:151], v[100:115]
	s_waitcnt lgkmcnt(2)
	v_mfma_f32_32x32x16_bf16 v[84:99], v[6:9], v[148:151], v[84:99]
	s_waitcnt vmcnt(0) lgkmcnt(1)
	v_mfma_f32_32x32x16_bf16 v[100:115], v[10:13], v[144:147], v[100:115]
	s_waitcnt lgkmcnt(0)
	v_mfma_f32_32x32x16_bf16 v[84:99], v[80:83], v[144:147], v[84:99]
	s_branch .LBB0_2857

.LBB0_2865:
	v_cndmask_b32_e64 v234, v1, v192, s[40:41]
	v_mul_f32_e32 v192, 0xbe0293ee, v234
	v_fmamk_f32 v1, v100, 0x3e0293ee, v192
	v_fmamk_f32 v2, v101, 0x3e0293ee, v192
	v_fmamk_f32 v3, v102, 0x3e0293ee, v192
	v_fmamk_f32 v4, v103, 0x3e0293ee, v192
	v_fmamk_f32 v5, v104, 0x3e0293ee, v192
	v_fmamk_f32 v6, v105, 0x3e0293ee, v192
	v_fmamk_f32 v7, v106, 0x3e0293ee, v192
	v_fmamk_f32 v8, v107, 0x3e0293ee, v192
	v_fmamk_f32 v9, v108, 0x3e0293ee, v192
	v_fmamk_f32 v10, v109, 0x3e0293ee, v192
	v_fmamk_f32 v11, v110, 0x3e0293ee, v192
	v_fmamk_f32 v12, v111, 0x3e0293ee, v192
	v_fmamk_f32 v13, v112, 0x3e0293ee, v192
	v_fmamk_f32 v14, v113, 0x3e0293ee, v192
	v_fmamk_f32 v15, v114, 0x3e0293ee, v192
	v_fmamk_f32 v112, v115, 0x3e0293ee, v192
	v_fmamk_f32 v100, v84, 0x3e0293ee, v192
	v_fmamk_f32 v101, v85, 0x3e0293ee, v192
	v_fmamk_f32 v102, v86, 0x3e0293ee, v192
	v_fmamk_f32 v103, v87, 0x3e0293ee, v192
	v_fmamk_f32 v104, v88, 0x3e0293ee, v192
	v_fmamk_f32 v105, v89, 0x3e0293ee, v192
	v_fmamk_f32 v106, v90, 0x3e0293ee, v192
	v_fmamk_f32 v107, v91, 0x3e0293ee, v192
	v_fmamk_f32 v108, v92, 0x3e0293ee, v192
	v_fmamk_f32 v109, v93, 0x3e0293ee, v192
	v_fmamk_f32 v110, v94, 0x3e0293ee, v192
	v_fmamk_f32 v111, v95, 0x3e0293ee, v192
	v_exp_f32_e32 v80, v1
	v_exp_f32_e32 v81, v2
	v_exp_f32_e32 v82, v3
	v_exp_f32_e32 v83, v4
	v_exp_f32_e32 v84, v5
	v_exp_f32_e32 v85, v6
	v_exp_f32_e32 v86, v7
	v_exp_f32_e32 v87, v8
	v_exp_f32_e32 v88, v9
	v_exp_f32_e32 v89, v10
	v_exp_f32_e32 v90, v11
	v_exp_f32_e32 v91, v12
	v_exp_f32_e32 v92, v13
	v_exp_f32_e32 v93, v14
	v_exp_f32_e32 v94, v15
	v_exp_f32_e32 v95, v112
	v_fmamk_f32 v193, v96, 0x3e0293ee, v192
	v_fmamk_f32 v194, v97, 0x3e0293ee, v192
	v_fmamk_f32 v195, v98, 0x3e0293ee, v192
	v_fmac_f32_e32 v192, 0x3e0293ee, v99
	s_waitcnt lgkmcnt(0)
	s_barrier
	s_and_b64 vcc, exec, s[38:39]
	s_cbranch_vccnz .LBB0_2867
	ds_read_b128 v[128:131], v224 offset:256
	ds_read_b128 v[132:135], v224 offset:288
	ds_read_b128 v[136:139], v224 offset:320
	ds_read_b128 v[140:143], v224 offset:352
	ds_read_b128 v[112:115], v224 offset:384
	ds_read_b128 v[116:119], v224 offset:416
	ds_read_b128 v[120:123], v224 offset:448
	ds_read_b128 v[124:127], v224 offset:480
	ds_read_b128 v[2:5], v226 offset:32768
	ds_read_b128 v[6:9], v226 offset:40960
	ds_read_b128 v[10:13], v227 offset:32768
	ds_read_b128 v[96:99], v227 offset:40960
	ds_read_b128 v[236:239], v228 offset:32768
	ds_read_b128 v[240:243], v228 offset:40960
	s_waitcnt lgkmcnt(5)
	v_mfma_f32_32x32x16_bf16 v[128:143], v[2:5], v[172:175], v[128:143]
	ds_read_b128 v[2:5], v229 offset:32768
	s_waitcnt lgkmcnt(5)
	v_mfma_f32_32x32x16_bf16 v[112:127], v[6:9], v[172:175], v[112:127]
	ds_read_b128 v[6:9], v229 offset:40960
	s_waitcnt lgkmcnt(5)
	v_mfma_f32_32x32x16_bf16 v[128:143], v[10:13], v[168:171], v[128:143]
	ds_read_b128 v[10:13], v226 offset:32896
	s_waitcnt lgkmcnt(5)
	v_mfma_f32_32x32x16_bf16 v[112:127], v[96:99], v[168:171], v[112:127]
	ds_read_b128 v[96:99], v226 offset:41088
	s_waitcnt lgkmcnt(5)
	v_mfma_f32_32x32x16_bf16 v[128:143], v[236:239], v[164:167], v[128:143]
	ds_read_b128 v[236:239], v227 offset:32896
	s_waitcnt lgkmcnt(5)
	v_mfma_f32_32x32x16_bf16 v[112:127], v[240:243], v[164:167], v[112:127]
	ds_read_b128 v[240:243], v227 offset:41088
	s_waitcnt lgkmcnt(5)
	v_mfma_f32_32x32x16_bf16 v[128:143], v[2:5], v[160:163], v[128:143]
	ds_read_b128 v[2:5], v228 offset:32896
	s_waitcnt lgkmcnt(5)
	v_mfma_f32_32x32x16_bf16 v[112:127], v[6:9], v[160:163], v[112:127]
	ds_read_b128 v[6:9], v228 offset:41088
	s_waitcnt lgkmcnt(5)
	v_mfma_f32_32x32x16_bf16 v[128:143], v[10:13], v[156:159], v[128:143]
	ds_read_b128 v[10:13], v229 offset:32896
	s_waitcnt lgkmcnt(5)
	v_mfma_f32_32x32x16_bf16 v[112:127], v[96:99], v[156:159], v[112:127]
	ds_read_b128 v[96:99], v229 offset:41088
	s_waitcnt lgkmcnt(5)
	v_mfma_f32_32x32x16_bf16 v[128:143], v[236:239], v[152:155], v[128:143]
	s_waitcnt lgkmcnt(4)
	v_mfma_f32_32x32x16_bf16 v[112:127], v[240:243], v[152:155], v[112:127]
	s_waitcnt lgkmcnt(3)
	v_mfma_f32_32x32x16_bf16 v[128:143], v[2:5], v[148:151], v[128:143]
	s_waitcnt lgkmcnt(2)
	v_mfma_f32_32x32x16_bf16 v[112:127], v[6:9], v[148:151], v[112:127]
	s_waitcnt lgkmcnt(1)
	v_mfma_f32_32x32x16_bf16 v[128:143], v[10:13], v[144:147], v[128:143]
	s_waitcnt lgkmcnt(0)
	v_mfma_f32_32x32x16_bf16 v[112:127], v[96:99], v[144:147], v[112:127]
	s_branch .LBB0_2868
